# grid barrier: non-leader pollers sleep 32 between polls
# baseline (speedup 1.0000x reference)
; __device__ __forceinline__ unsigned xb_ld(unsigned* p)              { return __hip_atomic_load(p, __ATOMIC_RELAXED, __HIP_MEMORY_SCOPE_AGENT); }
; #define XB_SPIN(cond, bar) do { unsigned _sp = 0; while (cond) { __builtin_amdgcn_s_sleep(1); \
;     if ((++_sp & 255u) == 0u) { if (xb_ld(&(bar)[XB_TMO])) break; if (_sp > XB_SPIN_CAP) { atomicAdd(&(bar)[XB_TMO], 1u); break; } } } } while (0)
; __device__ __forceinline__ void xcd_barrier(const XcdBarrier& b) {
;     ...
;             XB_SPIN(xb_ld(&bar[XB_XGEN(b.x)]) == gen, bar);
.LBB0_81:
	s_and_b32 s14, s18, 0xff
	s_mov_b64 s[12:13], -1
	s_cmp_lg_u32 s14, 0
	s_mov_b64 s[44:45], -1
	s_sleep 32
	s_cbranch_scc0 .LBB0_84
	s_and_b64 vcc, exec, s[44:45]
	s_cbranch_vccz .LBB0_80

; __device__ __forceinline__ unsigned xb_ld(unsigned* p)              { return __hip_atomic_load(p, __ATOMIC_RELAXED, __HIP_MEMORY_SCOPE_AGENT); }
; #define XB_SPIN(cond, bar) do { unsigned _sp = 0; while (cond) { __builtin_amdgcn_s_sleep(1); \
;     if ((++_sp & 255u) == 0u) { if (xb_ld(&(bar)[XB_TMO])) break; if (_sp > XB_SPIN_CAP) { atomicAdd(&(bar)[XB_TMO], 1u); break; } } } } while (0)
; __device__ __forceinline__ void xcd_barrier(const XcdBarrier& b) {
;     ...
;             XB_SPIN(xb_ld(&bar[XB_XGEN(b.x)]) == gen, bar);
.LBB0_364:
	s_and_b32 s14, s18, 0xff
	s_mov_b64 s[12:13], -1
	s_cmp_lg_u32 s14, 0
	s_mov_b64 s[78:79], -1
	s_sleep 32
	s_cbranch_scc0 .LBB0_367
	s_and_b64 vcc, exec, s[78:79]
	s_cbranch_vccz .LBB0_363

; __device__ __forceinline__ unsigned xb_ld(unsigned* p)              { return __hip_atomic_load(p, __ATOMIC_RELAXED, __HIP_MEMORY_SCOPE_AGENT); }
; #define XB_SPIN(cond, bar) do { unsigned _sp = 0; while (cond) { __builtin_amdgcn_s_sleep(1); \
;     if ((++_sp & 255u) == 0u) { if (xb_ld(&(bar)[XB_TMO])) break; if (_sp > XB_SPIN_CAP) { atomicAdd(&(bar)[XB_TMO], 1u); break; } } } } while (0)
; __device__ __forceinline__ void xcd_barrier(const XcdBarrier& b) {
;     ...
;             XB_SPIN(xb_ld(&bar[XB_XGEN(b.x)]) == gen, bar);
.LBB0_487:
	s_and_b32 s14, s18, 0xff
	s_mov_b64 s[12:13], -1
	s_cmp_lg_u32 s14, 0
	s_mov_b64 s[58:59], -1
	s_sleep 32
	s_cbranch_scc0 .LBB0_490
	s_and_b64 vcc, exec, s[58:59]
	s_cbranch_vccz .LBB0_486

; __device__ __forceinline__ unsigned xb_ld(unsigned* p)              { return __hip_atomic_load(p, __ATOMIC_RELAXED, __HIP_MEMORY_SCOPE_AGENT); }
; #define XB_SPIN(cond, bar) do { unsigned _sp = 0; while (cond) { __builtin_amdgcn_s_sleep(1); \
;     if ((++_sp & 255u) == 0u) { if (xb_ld(&(bar)[XB_TMO])) break; if (_sp > XB_SPIN_CAP) { atomicAdd(&(bar)[XB_TMO], 1u); break; } } } } while (0)
; __device__ __forceinline__ void xcd_barrier(const XcdBarrier& b) {
;     ...
;             XB_SPIN(xb_ld(&bar[XB_XGEN(b.x)]) == gen, bar);
.LBB0_582:
	s_and_b32 s14, s18, 0xff
	s_mov_b64 s[12:13], -1
	s_cmp_lg_u32 s14, 0
	s_mov_b64 s[54:55], -1
	s_sleep 32
	s_cbranch_scc0 .LBB0_585
	s_and_b64 vcc, exec, s[54:55]
	s_cbranch_vccz .LBB0_581

; __device__ __forceinline__ unsigned xb_ld(unsigned* p)              { return __hip_atomic_load(p, __ATOMIC_RELAXED, __HIP_MEMORY_SCOPE_AGENT); }
; #define XB_SPIN(cond, bar) do { unsigned _sp = 0; while (cond) { __builtin_amdgcn_s_sleep(1); \
;     if ((++_sp & 255u) == 0u) { if (xb_ld(&(bar)[XB_TMO])) break; if (_sp > XB_SPIN_CAP) { atomicAdd(&(bar)[XB_TMO], 1u); break; } } } } while (0)
; __device__ __forceinline__ void xcd_barrier(const XcdBarrier& b) {
;     ...
;             XB_SPIN(xb_ld(&bar[XB_XGEN(b.x)]) == gen, bar);
.LBB0_783:
	s_and_b32 s14, s19, 0xff
	s_mov_b64 s[12:13], -1
	s_cmp_lg_u32 s14, 0
	s_mov_b64 s[54:55], -1
	s_sleep 32
	s_cbranch_scc0 .LBB0_786
	s_and_b64 vcc, exec, s[54:55]
	s_cbranch_vccz .LBB0_782

; __device__ __forceinline__ unsigned xb_ld(unsigned* p)              { return __hip_atomic_load(p, __ATOMIC_RELAXED, __HIP_MEMORY_SCOPE_AGENT); }
; #define XB_SPIN(cond, bar) do { unsigned _sp = 0; while (cond) { __builtin_amdgcn_s_sleep(1); \
;     if ((++_sp & 255u) == 0u) { if (xb_ld(&(bar)[XB_TMO])) break; if (_sp > XB_SPIN_CAP) { atomicAdd(&(bar)[XB_TMO], 1u); break; } } } } while (0)
; __device__ __forceinline__ void xcd_barrier(const XcdBarrier& b) {
;     ...
;             XB_SPIN(xb_ld(&bar[XB_XGEN(b.x)]) == gen, bar);
.LBB0_884:
	s_and_b32 s14, s21, 0xff
	s_mov_b64 s[12:13], -1
	s_cmp_lg_u32 s14, 0
	s_mov_b64 s[34:35], -1
	s_sleep 32
	s_cbranch_scc0 .LBB0_887
	s_and_b64 vcc, exec, s[34:35]
	s_cbranch_vccz .LBB0_883

; __device__ __forceinline__ unsigned xb_ld(unsigned* p)              { return __hip_atomic_load(p, __ATOMIC_RELAXED, __HIP_MEMORY_SCOPE_AGENT); }
; #define XB_SPIN(cond, bar) do { unsigned _sp = 0; while (cond) { __builtin_amdgcn_s_sleep(1); \
;     if ((++_sp & 255u) == 0u) { if (xb_ld(&(bar)[XB_TMO])) break; if (_sp > XB_SPIN_CAP) { atomicAdd(&(bar)[XB_TMO], 1u); break; } } } } while (0)
; __device__ __forceinline__ void xcd_barrier(const XcdBarrier& b) {
;     ...
;             XB_SPIN(xb_ld(&bar[XB_XGEN(b.x)]) == gen, bar);
.LBB0_971:
	s_and_b32 s14, s20, 0xff
	s_mov_b64 s[12:13], -1
	s_cmp_lg_u32 s14, 0
	s_mov_b64 s[48:49], -1
	s_sleep 32
	s_cbranch_scc0 .LBB0_974
	s_and_b64 vcc, exec, s[48:49]
	s_cbranch_vccz .LBB0_970

; __device__ __forceinline__ unsigned xb_ld(unsigned* p)              { return __hip_atomic_load(p, __ATOMIC_RELAXED, __HIP_MEMORY_SCOPE_AGENT); }
; #define XB_SPIN(cond, bar) do { unsigned _sp = 0; while (cond) { __builtin_amdgcn_s_sleep(1); \
;     if ((++_sp & 255u) == 0u) { if (xb_ld(&(bar)[XB_TMO])) break; if (_sp > XB_SPIN_CAP) { atomicAdd(&(bar)[XB_TMO], 1u); break; } } } } while (0)
; __device__ __forceinline__ void xcd_barrier(const XcdBarrier& b) {
;     ...
;             XB_SPIN(xb_ld(&bar[XB_XGEN(b.x)]) == gen, bar);
.LBB0_1039:
	s_and_b32 s22, s3, 0xff
	s_mov_b64 s[12:13], -1
	s_cmp_lg_u32 s22, 0
	s_mov_b64 s[24:25], -1
	s_sleep 32
	s_cbranch_scc0 .LBB0_1042
	s_and_b64 vcc, exec, s[24:25]
	s_cbranch_vccz .LBB0_1038
